# attention: next item's Q fragments also prefetched (global loads issued after the item's last QK), K/V chunks 0-1 via LDS-DMA stage, sink via scalar load; loop entry no longer waits on vmcnt
# speedup vs baseline: 1.0025x; 1.0025x over previous
; __device__ __forceinline__ void attn_mfma(PP p, unsigned char* shm, int wv) {
;     ...
;         bf16x8 qf[2][4];
; #pragma unroll
;         for (int qi = 0; qi < 2; ++qi)
; #pragma unroll
;             for (int st = 0; st < 4; ++st) qf[qi][st] = *(const bf16x8*)(proj + (size_t)(qrow0 + 32 * qi + l31) * DIN + 1024 + 64 * hq + 16 * st + 8 * hl);
;         const float sink2 = p->attn_sink[hq] * L2E;
;         float mrun[2] = {sink2, sink2};
;         float lrun[2] = {hl == 0 ? 1.f : 0.f, hl == 0 ? 1.f : 0.f};
;         f32x16 oacc[2][2];
; #pragma unroll
;         for (int a = 0; a < 2; ++a)
; #pragma unroll
;             for (int c = 0; c < 2; ++c)
; #pragma unroll
;                 for (int i = 0; i < 16; ++i) oacc[a][c][i] = 0.f;
;         u32x4 kreg[2], vreg[2];
;         int ci = (qb == 0) ? 1 : 0;
;     ...
;         ATT_GLOAD(ci);
;         __syncthreads();
;         ATT_STAGE(0);
;         { const int c1 = ATT_NEXT(ci); if (c1 < 5) ATT_GLOAD(c1); }
.Lattn_pf_sk2:
	s_cmp_eq_u32 s97, 1
	s_cbranch_scc1 .Lattn_pf_sq1
	global_load_dwordx4 v[82:85], v[18:19], off offset:2048
	global_load_dwordx4 v[86:89], v[18:19], off offset:2080
	global_load_dwordx4 v[90:93], v[18:19], off offset:2112
	global_load_dwordx4 v[94:97], v[18:19], off offset:2144
.Lattn_pf_sq1:
	v_lshl_add_u64 v[18:19], v[20:21], 0, v[170:171]
	s_cmp_eq_u32 s97, 1
	s_cbranch_scc1 .Lattn_pf_sq2
	global_load_dwordx4 v[98:101], v[18:19], off offset:2048
	global_load_dwordx4 v[102:105], v[18:19], off offset:2080
	global_load_dwordx4 v[106:109], v[18:19], off offset:2112
	global_load_dwordx4 v[110:113], v[18:19], off offset:2144
.Lattn_pf_sq2:
	v_add_u32_e32 v18, s4, v24
	v_lshlrev_b32_e32 v18, 7, v18
	v_add_u32_e32 v20, s17, v18
	v_add_u32_e32 v18, v20, v182
	v_mad_i64_i32 v[18:19], s[4:5], v18, s30, v[168:169]
	v_lshl_add_u64 v[18:19], v[18:19], 0, s[6:7]
	v_lshl_add_u64 v[18:19], v[18:19], 0, v[172:173]
	s_waitcnt vmcnt(63) expcnt(7) lgkmcnt(15)
	s_barrier
	s_cmp_eq_u32 s97, 1
	s_cbranch_scc1 .Lattn_pf_sk3
	global_load_dwordx4 v[114:117], v[18:19], off offset:3072
	global_load_dwordx4 v[118:121], v[18:19], off offset:3328

; __device__ __forceinline__ void attn_mfma(PP p, unsigned char* shm, int wv) {
;     ...
;         ATT_GLOAD(ci);
;         __syncthreads();
;         ATT_STAGE(0);
;         { const int c1 = ATT_NEXT(ci); if (c1 < 5) ATT_GLOAD(c1); }
;         __syncthreads();
;         int par = 0;
;         while (ci < 5) {
;             const int cn = ATT_NEXT(ci);
;             if (cn < 5) { ATT_STAGE(par ^ 1); const int c2 = ATT_NEXT(cn); if (c2 < 5) ATT_GLOAD(c2); }
;             const bf16_t* Ks = (const bf16_t*)(shm + par * 36864);
;             const bf16_t* Vt = (const bf16_t*)(shm + par * 36864 + 18432);
;             const int kt_lo = (ci == 0 && qh == 1) ? 2 : 0, kt_hi = (ci == 2 && qh == 0) ? 2 : 4;
; #pragma unroll 1
;             for (int kt = kt_lo; kt < kt_hi; ++kt) {
;                 bf16x8 kf[4];
; #pragma unroll
;                 for (int st = 0; st < 4; ++st) kf[st] = *(const bf16x8*)(Ks + (32 * kt + l31) * 72 + 16 * st + 8 * hl);
;                 bf16x8 vf[2][2];
; #pragma unroll
;                 for (int db = 0; db < 2; ++db)
; #pragma unroll
;                     for (int s2 = 0; s2 < 2; ++s2) {
;                         const bf16_t* vp = Vt + (32 * db + l31) * 132 + 32 * kt + 16 * s2 + 4 * hl;
;                         const u32x2 lo = *(const u32x2*)vp, hi = *(const u32x2*)(vp + 8);
;                         u32x4 w; w.x = lo.x; w.y = lo.y; w.z = hi.x; w.w = hi.y;
;                         vf[db][s2] = __builtin_bit_cast(bf16x8, w);
;                     }
; #pragma unroll
;                 for (int qi = 0; qi < 2; ++qi) {
;                     f32x16 s;
; #pragma unroll
;                     for (int i = 0; i < 16; ++i) s[i] = 0.f;
;                     __builtin_amdgcn_s_setprio(1);
; #pragma unroll
;                     for (int st = 0; st < 4; ++st) s = __builtin_amdgcn_mfma_f32_32x32x16_bf16(kf[st], qf[qi][st], s, 0, 0, 0);
.LBB0_460:
	s_cmp_eq_u32 s38, 0
	s_cselect_b64 s[16:17], -1, 0
	s_cmp_lg_u32 s38, 0
	s_cselect_b64 s[18:19], -1, 0
	s_and_b64 s[20:21], s[10:11], s[16:17]
	s_and_b64 s[20:21], s[20:21], exec
	s_cselect_b32 s40, 2, 0
	s_cmp_eq_u32 s38, 2
	s_cselect_b64 s[20:21], -1, 0
	s_and_b64 s[20:21], s[12:13], s[20:21]
	s_and_b64 s[20:21], s[20:21], exec
	s_cselect_b32 s41, 2, 4
	s_cmp_ge_u32 s40, s41
	s_cbranch_scc1 .LBB0_487
	s_mul_i32 s20, s6, 0x9000
	s_lshl_b32 s21, s40, 6
	s_or_b32 s21, s20, s21
	v_add_u32_e32 v199, s21, v187
	s_mul_i32 s21, s40, 0x1200
	s_add_i32 s20, s20, s21
	v_add_u32_e32 v200, s20, v188
	v_lshl_add_u32 v201, s40, 5, v189
	s_cmp_eq_u32 s38, 0
	s_cbranch_scc1 .Lattn_p_entry_m0
	s_cmp_eq_u32 s38, 2
	s_cbranch_scc1 .Lattn_p_entry_m2
	s_cmp_lg_u32 s38, 4
	s_cbranch_scc1 .Lattn_p_entry_u
	s_add_i32 s98, s34, s24
	s_cmpk_gt_i32 s98, 0x1ff
	s_cbranch_scc1 .Lattn_p_entry_u
	s_bfe_u32 s100, s98, 0x70001
	s_lshl_b32 s100, s100, 7
	s_lshl_b32 s101, s98, 6
	s_and_b32 s101, s101, 0xffffc000
	s_or_b32 s100, s100, s101
	v_or_b32_e32 v230, s100, v180
	v_or_b32_e32 v231, 32, v230
	s_and_b32 s100, s98, 1
	s_lshl_b32 s100, s100, 2
	s_add_i32 s100, s100, s27
	s_lshl_b32 s100, s100, 7
	s_mov_b32 s101, 0
	v_mad_i64_i32 v[252:253], vcc, v230, s30, v[168:169]
	v_mad_i64_i32 v[254:255], vcc, v231, s30, v[168:169]
	v_lshl_add_u64 v[252:253], v[252:253], 0, s[100:101]
	v_lshl_add_u64 v[254:255], v[254:255], 0, s[100:101]
	v_lshl_add_u64 v[252:253], v[252:253], 0, v[170:171]
	v_lshl_add_u64 v[254:255], v[254:255], 0, v[170:171]
	s_bfe_u32 s100, s98, 0x70001
	s_add_i32 s100, s100, -1
	s_max_i32 s100, s100, 0
	s_lshl_b32 s100, s100, 7
	s_lshl_b32 s101, s98, 6
	s_and_b32 s101, s101, 0xffffc000
	s_add_i32 s100, s100, s101
	s_and_b32 s98, s98, 1
	s_lshl_b32 s98, s98, 7
	s_addk_i32 s98, 0xc00
	s_mov_b32 s99, 0
	v_add_u32_e32 v220, s100, v182
	v_add_u32_e32 v221, s100, v183
	v_mad_i64_i32 v[222:223], s[100:101], v220, s30, v[168:169]
	v_mad_i64_i32 v[226:227], s[100:101], v221, s30, v[168:169]
	v_lshl_add_u64 v[222:223], v[222:223], 0, v[172:173]
	v_lshl_add_u64 v[226:227], v[226:227], 0, v[172:173]
	v_lshl_add_u64 v[222:223], v[222:223], 0, s[98:99]
	v_lshl_add_u64 v[226:227], v[226:227], 0, s[98:99]
	s_movk_i32 s98, 0x100
	v_lshl_add_u64 v[224:225], v[222:223], 0, s[98:99]
	v_lshl_add_u64 v[228:229], v[226:227], 0, s[98:99]
	s_lshl_b32 s101, s33, 6
	s_add_i32 s101, s101, 0x12000
	s_mov_b32 m0, s101
	s_nop 0
	global_load_lds_dwordx4 v[222:223], off
	s_add_i32 m0, s101, 0x400
	s_nop 0
	global_load_lds_dwordx4 v[224:225], off
	s_add_i32 m0, s101, 0x800
	s_nop 0
	global_load_lds_dwordx4 v[226:227], off
	s_add_i32 m0, s101, 0xc00
	s_nop 0
	global_load_lds_dwordx4 v[228:229], off
	s_mov_b32 s98, 0x70000
	v_lshl_add_u64 v[222:223], v[222:223], 0, s[98:99]
	v_lshl_add_u64 v[224:225], v[224:225], 0, s[98:99]
	v_lshl_add_u64 v[226:227], v[226:227], 0, s[98:99]
	v_lshl_add_u64 v[228:229], v[228:229], 0, s[98:99]
	s_add_i32 m0, s101, 0x8000
	s_nop 0
	global_load_lds_dwordx4 v[222:223], off
	s_add_i32 m0, s101, 0x8400
	s_nop 0
	global_load_lds_dwordx4 v[224:225], off
	s_add_i32 m0, s101, 0x8800
	s_nop 0
	global_load_lds_dwordx4 v[226:227], off
	s_add_i32 m0, s101, 0x8c00
	s_nop 0
	global_load_lds_dwordx4 v[228:229], off
	s_add_i32 s100, s34, s24
	s_and_b32 s100, s100, 1
	s_lshl_b32 s100, s100, 2
	s_add_i32 s100, s100, s27
	s_lshl_b32 s100, s100, 2
	s_load_dword s100, s[8:9], s100
	s_waitcnt lgkmcnt(0)
	s_mov_b32 s97, 1
	s_branch .Lattn_p_entry_u
.Lattn_p_entry_m0:
	s_bfe_u32 s28, s56, 0x10006
	s_lshl_b32 s28, s28, 1
	ds_read_b128 v[158:161], v200
	ds_read_b128 v[154:157], v200 offset:32
	ds_read_b128 v[150:153], v200 offset:64
	ds_read_b128 v[146:149], v200 offset:96
	v_add_u32_e32 v200, 0x1200, v200
	s_add_i32 s20, s41, -1
	s_waitcnt lgkmcnt(3)
	v_mfma_f32_32x32x16_bf16 v[66:81], v[158:161], v[82:85], 0
	s_waitcnt lgkmcnt(2)
	v_mfma_f32_32x32x16_bf16 v[66:81], v[154:157], v[86:89], v[66:81]
	s_waitcnt lgkmcnt(1)
	v_mfma_f32_32x32x16_bf16 v[66:81], v[150:153], v[90:93], v[66:81]
	s_waitcnt lgkmcnt(0)
	v_mfma_f32_32x32x16_bf16 v[66:81], v[146:149], v[94:97], v[66:81]
	s_nop 4
	s_cmp_ge_u32 s40, s20
	s_cbranch_scc1 .Lattn_p_last_m0

; __device__ __forceinline__ void attn_mfma(PP p, unsigned char* shm, int wv) {
;     ...
;                 bf16x8 kf[4];
; #pragma unroll
;                 for (int st = 0; st < 4; ++st) kf[st] = *(const bf16x8*)(Ks + (32 * kt + l31) * 72 + 16 * st + 8 * hl);
;                 bf16x8 vf[2][2];
; #pragma unroll
;                 for (int db = 0; db < 2; ++db)
; #pragma unroll
;                     for (int s2 = 0; s2 < 2; ++s2) {
;                         const bf16_t* vp = Vt + (32 * db + l31) * 132 + 32 * kt + 16 * s2 + 4 * hl;
;                         const u32x2 lo = *(const u32x2*)vp, hi = *(const u32x2*)(vp + 8);
;                         u32x4 w; w.x = lo.x; w.y = lo.y; w.z = hi.x; w.w = hi.y;
;                         vf[db][s2] = __builtin_bit_cast(bf16x8, w);
;                     }
; #pragma unroll
;                 for (int qi = 0; qi < 2; ++qi) {
;                     f32x16 s;
; #pragma unroll
;                     for (int i = 0; i < 16; ++i) s[i] = 0.f;
;                     __builtin_amdgcn_s_setprio(1);
; #pragma unroll
;                     for (int st = 0; st < 4; ++st) s = __builtin_amdgcn_mfma_f32_32x32x16_bf16(kf[st], qf[qi][st], s, 0, 0, 0);
.Lattn_p_entry_u:
	ds_read_b128 v[158:161], v200
	ds_read_b128 v[154:157], v200 offset:32
	ds_read_b128 v[150:153], v200 offset:64
	ds_read_b128 v[146:149], v200 offset:96
	v_add_u32_e32 v200, 0x1200, v200
	s_add_i32 s20, s41, -1
	s_waitcnt lgkmcnt(3)
	v_mfma_f32_32x32x16_bf16 v[66:81], v[158:161], v[82:85], 0
	s_waitcnt lgkmcnt(2)
	v_mfma_f32_32x32x16_bf16 v[66:81], v[154:157], v[86:89], v[66:81]
	s_waitcnt lgkmcnt(1)
	v_mfma_f32_32x32x16_bf16 v[66:81], v[150:153], v[90:93], v[66:81]
	s_waitcnt lgkmcnt(0)
	v_mfma_f32_32x32x16_bf16 v[66:81], v[146:149], v[94:97], v[66:81]
	s_nop 4
	s_cmp_ge_u32 s40, s20
	s_cbranch_scc1 .Lattn_p_last_u

; __device__ __forceinline__ unsigned cvt_pk_bf16(float lo, float hi) { unsigned r; asm("v_cvt_pk_bf16_f32 %0, %1, %2" : "=v"(r) : "v"(lo), "v"(hi)); return r; }
; __device__ __forceinline__ void attn_mfma(PP p, unsigned char* shm, int wv) {
;     ...
;             for (int st = 0; st < 4; ++st) qf[qi][st] = *(const bf16x8*)(proj + (size_t)(qrow0 + 32 * qi + l31) * DIN + 1024 + 64 * hq + 16 * st + 8 * hl);
;     ...
;                     float mx = s[0];
; #pragma unroll
;                     for (int i = 1; i < 16; ++i) mx = fmaxf(mx, s[i]);
;                     mx = fmaxf(mx, __shfl_xor(mx, 32));
;                     const float mnew = fmaxf(mrun[qi], mx * SC2);
;                     if (__builtin_amdgcn_ballot_w64(mnew > mrun[qi]) != 0ull) {
;                         const float alpha = __builtin_amdgcn_exp2f(mrun[qi] - mnew);
;                         lrun[qi] *= alpha;
; #pragma unroll
;                         for (int db = 0; db < 2; ++db)
; #pragma unroll
;                             for (int i = 0; i < 16; ++i) oacc[db][qi][i] *= alpha;
;                         mrun[qi] = mnew;
;                     }
;                     float ls = 0.f;
; #pragma unroll
;                     for (int i = 0; i < 16; ++i) { s[i] = __builtin_amdgcn_exp2f(__builtin_fmaf(s[i], SC2, -mnew)); ls += s[i]; }
;                     lrun[qi] += ls;
;                     bf16x8 pf[2];
; #pragma unroll
;                     for (int s2 = 0; s2 < 2; ++s2) {
;                         u32x4 w; w.x = cvt_pk_bf16(s[8 * s2 + 0], s[8 * s2 + 1]); w.y = cvt_pk_bf16(s[8 * s2 + 2], s[8 * s2 + 3]);
;                         w.z = cvt_pk_bf16(s[8 * s2 + 4], s[8 * s2 + 5]); w.w = cvt_pk_bf16(s[8 * s2 + 6], s[8 * s2 + 7]);
;                         pf[s2] = __builtin_bit_cast(bf16x8, w);
;                     }
; #pragma unroll
;                     for (int db = 0; db < 2; ++db)
; #pragma unroll
;                         for (int s2 = 0; s2 < 2; ++s2) oacc[db][qi] = __builtin_amdgcn_mfma_f32_32x32x16_bf16(vf[db][s2], pf[s2], oacc[db][qi], 0, 0, 0);
.Lattn_p_nr0_bu:
	v_fma_f32 v236, v66, s31, -v248
	v_fma_f32 v237, v67, s31, -v248
	v_fma_f32 v238, v68, s31, -v248
	v_fma_f32 v239, v69, s31, -v248
	v_exp_f32_e32 v66, v236
	v_exp_f32_e32 v67, v237
	v_exp_f32_e32 v68, v238
	v_exp_f32_e32 v69, v239
	v_mfma_f32_32x32x16_bf16 v[220:235], v[150:153], v[106:109], v[220:235]
	v_fma_f32 v236, v70, s31, -v248
	v_fma_f32 v237, v71, s31, -v248
	v_fma_f32 v238, v72, s31, -v248
	v_fma_f32 v239, v73, s31, -v248
	v_exp_f32_e32 v70, v236
	v_exp_f32_e32 v71, v237
	v_exp_f32_e32 v72, v238
	v_exp_f32_e32 v73, v239
	v_fma_f32 v236, v74, s31, -v248
	v_fma_f32 v237, v75, s31, -v248
	v_fma_f32 v238, v76, s31, -v248
	v_fma_f32 v239, v77, s31, -v248
	v_exp_f32_e32 v74, v236
	v_exp_f32_e32 v75, v237
	v_exp_f32_e32 v76, v238
	v_exp_f32_e32 v77, v239
	v_mfma_f32_32x32x16_bf16 v[220:235], v[146:149], v[110:113], v[220:235]
	s_cmp_eq_u32 s97, 1
	s_cbranch_scc0 .Lattn_pf_noq
	global_load_dwordx4 v[82:85], v[252:253], off offset:2048
	global_load_dwordx4 v[86:89], v[252:253], off offset:2080
	global_load_dwordx4 v[90:93], v[252:253], off offset:2112
	global_load_dwordx4 v[94:97], v[252:253], off offset:2144
	global_load_dwordx4 v[98:101], v[254:255], off offset:2048
	global_load_dwordx4 v[102:105], v[254:255], off offset:2080
	global_load_dwordx4 v[106:109], v[254:255], off offset:2112
	global_load_dwordx4 v[110:113], v[254:255], off offset:2144
.Lattn_pf_noq:
	v_fma_f32 v236, v78, s31, -v248
	v_fma_f32 v237, v79, s31, -v248
	v_fma_f32 v238, v80, s31, -v248
	v_fma_f32 v239, v81, s31, -v248
	v_exp_f32_e32 v78, v236
	v_exp_f32_e32 v79, v237
	v_exp_f32_e32 v80, v238
	v_exp_f32_e32 v81, v239
	v_cvt_pk_bf16_f32 v204, v66, v67
	v_cvt_pk_bf16_f32 v205, v68, v69
	v_cvt_pk_bf16_f32 v206, v70, v71
	v_cvt_pk_bf16_f32 v207, v72, v73
	v_cvt_pk_bf16_f32 v208, v74, v75
	v_cvt_pk_bf16_f32 v209, v76, v77
	v_cvt_pk_bf16_f32 v210, v78, v79
	v_cvt_pk_bf16_f32 v211, v80, v81
	s_waitcnt lgkmcnt(0)
	v_mfma_f32_32x32x16_bf16 v[50:65], v[142:145], v[204:207], v[50:65]
	v_add_f32_e32 v250, 0, v66
	v_add_f32_e32 v250, v67, v250
	v_add_f32_e32 v250, v68, v250
	v_add_f32_e32 v250, v69, v250
	v_add_f32_e32 v250, v70, v250
	v_add_f32_e32 v250, v71, v250
	v_add_f32_e32 v250, v72, v250
	v_add_f32_e32 v250, v73, v250
	v_mfma_f32_32x32x16_bf16 v[34:49], v[134:137], v[204:207], v[34:49]
	v_add_f32_e32 v250, v74, v250
	v_add_f32_e32 v250, v75, v250
	v_add_f32_e32 v250, v76, v250
	v_add_f32_e32 v250, v77, v250
	v_add_f32_e32 v250, v78, v250
	v_add_f32_e32 v250, v79, v250
	v_add_f32_e32 v250, v80, v250
	v_add_f32_e32 v250, v81, v250
	v_add_f32_e32 v196, v250, v196
	v_mfma_f32_32x32x16_bf16 v[50:65], v[138:141], v[208:211], v[50:65]
	v_max3_f32 v246, v220, v221, v222
	v_max3_f32 v247, v223, v224, v225
	v_max3_f32 v246, v246, v226, v227
	v_max3_f32 v247, v247, v228, v229
	v_max3_f32 v246, v246, v230, v231
	v_max3_f32 v247, v247, v232, v233
	v_mfma_f32_32x32x16_bf16 v[34:49], v[130:133], v[208:211], v[34:49]
	v_max3_f32 v246, v246, v234, v235
	v_max_f32_e32 v246, v246, v247
	v_mov_b32_e32 v247, v246
	v_max_f32_e32 v249, v198, v198
	s_nop 0
	v_permlane32_swap_b32_e32 v246, v247
	v_max_f32_e32 v246, v246, v247
	v_mul_f32_e32 v246, 0x3e38aa3b, v246
	v_max_f32_e32 v249, v249, v246
	v_cmp_gt_f32_e32 vcc, v249, v198
	s_cbranch_vccz .Lattn_p_nr1_bu
	v_sub_f32_e32 v240, v198, v249
	v_exp_f32_e32 v240, v240
	v_mov_b32_e32 v198, v249
	v_mul_f32_e32 v1, v1, v240
	v_pk_mul_f32 v[32:33], v[32:33], v[240:241] op_sel_hi:[1,0]
	v_pk_mul_f32 v[30:31], v[30:31], v[240:241] op_sel_hi:[1,0]
	v_pk_mul_f32 v[28:29], v[28:29], v[240:241] op_sel_hi:[1,0]
	v_pk_mul_f32 v[26:27], v[26:27], v[240:241] op_sel_hi:[1,0]
	v_pk_mul_f32 v[24:25], v[24:25], v[240:241] op_sel_hi:[1,0]
	v_pk_mul_f32 v[22:23], v[22:23], v[240:241] op_sel_hi:[1,0]
	v_pk_mul_f32 v[20:21], v[20:21], v[240:241] op_sel_hi:[1,0]
	v_pk_mul_f32 v[18:19], v[18:19], v[240:241] op_sel_hi:[1,0]
	v_pk_mul_f32 v[16:17], v[16:17], v[240:241] op_sel_hi:[1,0]
	v_pk_mul_f32 v[14:15], v[14:15], v[240:241] op_sel_hi:[1,0]
	v_pk_mul_f32 v[12:13], v[12:13], v[240:241] op_sel_hi:[1,0]
	v_pk_mul_f32 v[10:11], v[10:11], v[240:241] op_sel_hi:[1,0]
	v_pk_mul_f32 v[8:9], v[8:9], v[240:241] op_sel_hi:[1,0]
	v_pk_mul_f32 v[6:7], v[6:7], v[240:241] op_sel_hi:[1,0]
	v_pk_mul_f32 v[4:5], v[4:5], v[240:241] op_sel_hi:[1,0]
	v_pk_mul_f32 v[2:3], v[2:3], v[240:241] op_sel_hi:[1,0]
